# pipelined K-split reduce + 3 percent of the copy moved from P7's epilogue to P5's
# speedup vs baseline: 1.0010x; 1.0010x over previous
.LBB0_661:
	s_lshl_b32 s64, s88, 11
	v_or_b32_e32 v0, s64, v222
	s_cmp_gt_i32 s88, 3
	v_add_u32_e32 v0, 0x1be800, v0
	s_mov_b32 s2, 0x36c800
	s_cselect_b64 s[0:1], -1, 0
	v_cmp_gt_i32_e32 vcc, s2, v0
	s_and_b64 s[2:3], s[0:1], vcc
	s_and_saveexec_b64 s[0:1], s[2:3]
	s_cbranch_execz .LBB0_664
	v_readlane_b32 s2, v247, 15
	v_add_u32_e32 v0, s64, v222
	s_add_i32 s6, s2, 0xffffe000
	v_add_u32_e32 v0, 0x1be800, v0
	s_mov_b64 s[2:3], 0
	s_mov_b32 s7, 0x80808081
	s_mov_b32 s8, 0xfffc0400
	s_movk_i32 s9, 0x4000
	s_mov_b32 s10, 0x36c7ff
.LBB0_663:
	s_waitcnt lgkmcnt(0)
	v_mul_hi_i32 v1, v0, s7
	v_min_i32_e32 v2, 0x36c5ff, v0
	v_min_i32_e32 v3, 0x36c3ff, v0
	v_min_i32_e32 v4, 0x36c1ff, v0
	v_add_u32_e32 v1, v1, v0
	v_add_u32_e32 v7, 0x200, v2
	v_add_u32_e32 v9, 0x400, v3
	v_add_u32_e32 v11, 0x600, v4
	v_lshrrev_b32_e32 v2, 31, v1
	v_ashrrev_i32_e32 v1, 17, v1
	v_mul_hi_i32 v3, v7, s7
	v_mul_hi_i32 v4, v9, s7
	v_mul_hi_i32 v5, v11, s7
	v_add_u32_e32 v2, v1, v2
	v_add_u32_e32 v1, v3, v7
	v_add_u32_e32 v6, v4, v9
	v_add_u32_e32 v5, v5, v11
	v_mad_i32_i24 v4, v2, s8, v0
	v_ashrrev_i32_e32 v3, 31, v2
	v_lshrrev_b32_e32 v8, 31, v1
	v_ashrrev_i32_e32 v1, 17, v1
	v_lshrrev_b32_e32 v10, 31, v6
	s_waitcnt vmcnt(9)
	v_ashrrev_i32_e32 v12, 17, v6
	v_lshrrev_b32_e32 v13, 31, v5
	v_ashrrev_i32_e32 v14, 17, v5
	v_lshlrev_b64 v[2:3], 18, v[2:3]
	v_ashrrev_i32_e32 v5, 31, v4
	v_add_u32_e32 v6, v1, v8
	v_add_u32_e32 v8, v12, v10
	v_add_u32_e32 v10, v14, v13
	v_lshl_add_u64 v[2:3], v[2:3], 0, v[4:5]
	v_mad_i32_i24 v4, v6, s8, v7
	v_ashrrev_i32_e32 v7, 31, v6
	v_mad_i32_i24 v12, v8, s8, v9
	v_ashrrev_i32_e32 v9, 31, v8
	v_mad_i32_i24 v14, v10, s8, v11
	v_ashrrev_i32_e32 v11, 31, v10
	s_waitcnt vmcnt(5)
	v_lshlrev_b64 v[34:35], 4, v[2:3]
	v_lshlrev_b64 v[2:3], 18, v[6:7]
	v_ashrrev_i32_e32 v5, 31, v4
	v_lshlrev_b64 v[6:7], 18, v[8:9]
	v_ashrrev_i32_e32 v13, 31, v12
	v_lshlrev_b64 v[8:9], 18, v[10:11]
	v_ashrrev_i32_e32 v15, 31, v14
	v_lshl_add_u64 v[10:11], s[82:83], 0, v[34:35]
	v_lshl_add_u64 v[2:3], v[2:3], 0, v[4:5]
	v_lshl_add_u64 v[4:5], v[6:7], 0, v[12:13]
	v_lshl_add_u64 v[6:7], v[8:9], 0, v[14:15]
	v_add_co_u32_e32 v8, vcc, s9, v10
	v_lshl_add_u64 v[16:17], s[84:85], 0, v[34:35]
	s_nop 0
	v_addc_co_u32_e32 v9, vcc, 0, v11, vcc
	s_waitcnt vmcnt(4)
	v_lshlrev_b64 v[36:37], 4, v[2:3]
	v_lshlrev_b64 v[40:41], 4, v[6:7]
	v_add_co_u32_e32 v6, vcc, s9, v16
	v_lshl_add_u64 v[10:11], s[82:83], 0, v[36:37]
	s_nop 0
	v_addc_co_u32_e32 v7, vcc, 0, v17, vcc
	v_add_co_u32_e32 v10, vcc, s9, v10
	v_lshl_add_u64 v[12:13], s[84:85], 0, v[36:37]
	s_nop 0
	v_addc_co_u32_e32 v11, vcc, 0, v11, vcc
	v_lshlrev_b64 v[38:39], 4, v[4:5]
	v_add_co_u32_e32 v16, vcc, s9, v12
	v_lshl_add_u64 v[14:15], s[82:83], 0, v[38:39]
	s_nop 0
	v_addc_co_u32_e32 v17, vcc, 0, v13, vcc
	v_add_co_u32_e32 v24, vcc, s9, v14
	v_lshl_add_u64 v[18:19], s[84:85], 0, v[38:39]
	s_nop 0
	v_addc_co_u32_e32 v25, vcc, 0, v15, vcc
	v_add_co_u32_e32 v26, vcc, s9, v18
	v_lshl_add_u64 v[20:21], s[82:83], 0, v[40:41]
	s_nop 0
	v_addc_co_u32_e32 v27, vcc, 0, v19, vcc
	v_add_co_u32_e32 v28, vcc, s9, v20
	v_lshl_add_u64 v[22:23], s[84:85], 0, v[40:41]
	s_nop 0
	v_addc_co_u32_e32 v29, vcc, 0, v21, vcc
	v_add_co_u32_e32 v30, vcc, s9, v22
	global_load_dwordx4 v[2:5], v[8:9], off nt
	s_nop 0
	v_addc_co_u32_e32 v31, vcc, 0, v23, vcc
	global_load_dwordx4 v[6:9], v[6:7], off nt
	s_nop 0
	global_load_dwordx4 v[10:13], v[10:11], off nt
	s_nop 0
	global_load_dwordx4 v[14:17], v[16:17], off nt
	s_nop 0
	global_load_dwordx4 v[18:21], v[24:25], off nt
	s_nop 0
	global_load_dwordx4 v[22:25], v[26:27], off nt
	s_nop 0
	global_load_dwordx4 v[26:29], v[28:29], off nt
	s_nop 0
	global_load_dwordx4 v[30:33], v[30:31], off nt
	v_add_u32_e32 v0, s6, v0
	v_cmp_lt_i32_e32 vcc, s10, v0
	s_or_b64 s[2:3], vcc, s[2:3]
	v_lshl_add_u64 v[42:43], s[70:71], 0, v[34:35]
	v_lshl_add_u64 v[34:35], s[66:67], 0, v[34:35]
	v_lshl_add_u64 v[44:45], s[70:71], 0, v[36:37]
	v_lshl_add_u64 v[36:37], s[66:67], 0, v[36:37]
	v_lshl_add_u64 v[46:47], s[70:71], 0, v[38:39]
	v_lshl_add_u64 v[38:39], s[66:67], 0, v[38:39]
	v_lshl_add_u64 v[48:49], s[70:71], 0, v[40:41]
	v_lshl_add_u64 v[40:41], s[66:67], 0, v[40:41]
	s_waitcnt vmcnt(7)
	global_store_dwordx4 v[42:43], v[2:5], off nt
	s_waitcnt vmcnt(7)
	global_store_dwordx4 v[34:35], v[6:9], off nt
	s_waitcnt vmcnt(7)
	global_store_dwordx4 v[44:45], v[10:13], off nt
	s_waitcnt vmcnt(7)
	global_store_dwordx4 v[36:37], v[14:17], off nt
	s_waitcnt vmcnt(7)
	global_store_dwordx4 v[46:47], v[18:21], off nt
	s_waitcnt vmcnt(7)
	global_store_dwordx4 v[38:39], v[22:25], off nt
	s_waitcnt vmcnt(7)
	global_store_dwordx4 v[48:49], v[26:29], off nt
	s_waitcnt vmcnt(7)
	global_store_dwordx4 v[40:41], v[30:33], off nt
	s_andn2_b64 exec, exec, s[2:3]
	s_cbranch_execnz .LBB0_663

.LBB0_1030:
	s_add_u32 s42, s24, 0x1e04000
	s_addc_u32 s43, s25, 0
	s_add_i32 s5, s26, -16
	s_cmp_gt_i32 s88, 15
	s_cselect_b32 s5, s5, 0
	s_lshl_b32 s44, s0, 6
	s_lshl_b32 s7, s0, 13
	s_lshl_b32 s0, s1, 5
	s_and_b32 s45, s0, 0x60
	s_lshl_b32 s14, s45, 7
	s_add_u32 s10, s24, 0x1c20000
	s_mov_b64 s[12:13], 0x80
	s_addc_u32 s11, s25, 0
	s_add_i32 m0, s36, 0x18000
	v_lshl_add_u64 v[6:7], v[6:7], 0, s[12:13]
	s_waitcnt vmcnt(2)
	s_barrier
	global_load_lds_dwordx4 v[6:7], off
	v_lshl_add_u64 v[4:5], v[4:5], 0, s[12:13]
	s_add_i32 m0, s36, 0x1a000
	s_add_i32 s46, s36, 0x8000
	s_add_i32 s47, s36, 0xa000
	global_load_lds_dwordx4 v[4:5], off
	v_lshl_add_u64 v[2:3], v[2:3], 0, s[12:13]
	s_mov_b32 m0, s46
	s_add_u32 s0, s34, 0xb0080
	global_load_lds_dwordx4 v[2:3], off
	v_lshl_add_u64 v[0:1], v[0:1], 0, s[12:13]
	s_mov_b32 m0, s47
	s_addc_u32 s1, s35, 0
	global_load_lds_dwordx4 v[0:1], off
	s_add_i32 m0, s36, 0x1c000
	v_lshl_add_u64 v[0:1], s[0:1], 0, v[194:195]
	global_load_lds_dwordx4 v[0:1], off
	v_lshl_add_u64 v[0:1], s[0:1], 0, v[198:199]
	s_add_i32 m0, s36, 0x1e000
	v_bfe_u32 v227, v8, 4, 2
	global_load_lds_dwordx4 v[0:1], off
	v_and_b32_e32 v226, 15, v8
	v_lshlrev_b32_e32 v0, 4, v227
	v_lshlrev_b32_e32 v1, 2, v8
	v_lshl_or_b32 v0, v226, 6, v0
	v_and_b32_e32 v1, 32, v1
	s_cmpk_lt_u32 s6, 0x100
	v_bitop3_b32 v2, v0, s7, v1 bitop3:0xde
	v_bitop3_b32 v228, v0, s14, v1 bitop3:0xde
	s_cselect_b64 s[14:15], -1, 0
	v_and_b32_e32 v0, 63, v222
	s_cmp_gt_i32 s5, 0
	v_cmp_eq_u32_e64 s[0:1], 0, v0
	s_cselect_b64 s[6:7], -1, 0
	s_addk_i32 s64, 0x8000
	v_or_b32_e32 v0, 0x36c800, v222
	v_add_u32_e32 v229, s64, v0
	s_mov_b32 s16, 0x501000
	v_cmp_gt_i32_e32 vcc, s16, v229
	s_lshl_b32 s48, s5, 11
	v_lshrrev_b32_e32 v1, 1, v9
	v_mul_lo_u32 v0, v11, s4
	s_mov_b32 s5, 0xb000
	s_and_b64 s[16:17], s[6:7], vcc
	v_mad_u64_u32 v[0:1], s[6:7], v1, s5, v[0:1]
	v_or_b32_e32 v0, v0, v10
	s_mov_b64 s[18:19], 0xb0080
	v_add_lshl_u32 v0, v0, v12, 1
	v_mov_b32_e32 v1, v195
	v_lshl_add_u64 v[200:201], v[0:1], 0, s[18:19]
	v_lshrrev_b32_e32 v1, 1, v13
	v_mul_lo_u32 v0, v14, s4
	v_mad_u64_u32 v[0:1], s[4:5], v1, s5, v[0:1]
	s_waitcnt vmcnt(6)
	v_or_b32_e32 v0, v0, v15
	v_add_lshl_u32 v0, v0, v16, 1
	v_mov_b32_e32 v1, v195
	s_add_i32 s49, 0, 0x10000
	s_add_i32 s50, 0, 0x14000
	v_readlane_b32 s64, v247, 11
	v_lshl_add_u64 v[202:203], v[0:1], 0, s[18:19]
	v_mov_b64_e32 v[204:205], 0x104
	v_mov_b64_e32 v[206:207], 0x103
	v_add_u32_e32 v230, s49, v228
	v_add_u32_e32 v231, s50, v228
	v_add_u32_e32 v232, 0, v2
	s_movk_i32 s51, 0x3fff
	v_mbcnt_hi_u32_b32 v233, -1, v223
	s_mov_b32 s52, 0x80808081
	s_mov_b32 s53, 0xfffc0400
	s_mov_b32 s54, 0x500fff
	v_mov_b32_e32 v234, 0x358637bd
	v_readlane_b32 s65, v247, 12
	s_barrier
	s_branch .LBB0_1033
